# grid barrier poll back-off: s_sleep 6 between polls of the arrival counter (was s_sleep 1)
# speedup vs baseline: 1.0034x; 1.0034x over previous
.Lxb0_spin:
	global_load_dword v3, v2, s[76:77] offset:1024 sc1
	s_waitcnt vmcnt(0)
	v_sub_u32_e32 v3, v3, v4
	v_cmp_gt_i32_e32 vcc, 0, v3
	s_cbranch_vccz .Lxb0_done
	s_sleep 6
	s_add_i32 s12, s12, 1
	s_and_b32 s13, s12, 0xff
	s_cmp_lg_u32 s13, 0
	s_cbranch_scc1 .Lxb0_spin
	v_mov_b32_e32 v0, 0x60000
	global_load_dword v3, v0, s[76:77] offset:512 sc1
	s_waitcnt vmcnt(0)
	v_cmp_ne_u32_e32 vcc, 0, v3
	s_cbranch_vccnz .Lxb0_done
	s_cmp_le_u32 s12, 0x400000
	s_cbranch_scc1 .Lxb0_spin
	v_mov_b32_e32 v3, 1
	global_atomic_add v0, v3, s[76:77] offset:512

.Lxb1_spin:
	global_load_dword v3, v2, s[76:77] offset:1024 sc1
	s_waitcnt vmcnt(0)
	v_sub_u32_e32 v3, v3, v4
	v_cmp_gt_i32_e32 vcc, 0, v3
	s_cbranch_vccz .Lxb1_done
	s_sleep 6
	s_add_i32 s8, s8, 1
	s_and_b32 s9, s8, 0xff
	s_cmp_lg_u32 s9, 0
	s_cbranch_scc1 .Lxb1_spin
	v_mov_b32_e32 v0, 0x60000
	global_load_dword v3, v0, s[76:77] offset:512 sc1
	s_waitcnt vmcnt(0)
	v_cmp_ne_u32_e32 vcc, 0, v3
	s_cbranch_vccnz .Lxb1_done
	s_cmp_le_u32 s8, 0x400000
	s_cbranch_scc1 .Lxb1_spin
	v_mov_b32_e32 v3, 1
	global_atomic_add v0, v3, s[76:77] offset:512

.Lxb3_spin:
	global_load_dword v3, v2, s[76:77] offset:1024 sc1
	s_waitcnt vmcnt(0)
	v_sub_u32_e32 v3, v3, v4
	v_cmp_gt_i32_e32 vcc, 0, v3
	s_cbranch_vccz .Lxb3_done
	s_sleep 6
	s_add_i32 s6, s6, 1
	s_and_b32 s7, s6, 0xff
	s_cmp_lg_u32 s7, 0
	s_cbranch_scc1 .Lxb3_spin
	v_mov_b32_e32 v0, 0x60000
	global_load_dword v3, v0, s[76:77] offset:512 sc1
	s_waitcnt vmcnt(0)
	v_cmp_ne_u32_e32 vcc, 0, v3
	s_cbranch_vccnz .Lxb3_done
	s_cmp_le_u32 s6, 0x400000
	s_cbranch_scc1 .Lxb3_spin
	v_mov_b32_e32 v3, 1
	global_atomic_add v0, v3, s[76:77] offset:512
